# grid barrier: XCD leader issues its cache invalidate right after its TOP arrival (its XCD is quiescent until release) instead of after the release poll
# baseline (speedup 1.0000x reference)
.LBB0_956:
	s_or_b64 exec, exec, s[16:17]
	buffer_inv sc1
	s_waitcnt vmcnt(0)
	v_readfirstlane_b32 s2, v2
	v_cvt_f32_u32_e32 v2, v0
	v_sub_u32_e32 v3, 0, v0
	v_add_u32_e32 v1, s2, v1
	v_readlane_b32 s8, v252, 9
	v_rcp_iflag_f32_e32 v2, v2
	v_readlane_b32 s9, v252, 10
	s_mov_b64 s[16:17], -1
	v_mul_f32_e32 v2, 0x4f7ffffe, v2
	v_cvt_u32_f32_e32 v2, v2
	v_mul_lo_u32 v3, v3, v2
	v_mul_hi_u32 v3, v2, v3
	v_add_u32_e32 v2, v2, v3
	v_mul_hi_u32 v2, v1, v2
	v_mul_lo_u32 v3, v2, v0
	v_sub_u32_e32 v3, v1, v3
	v_cmp_ge_u32_e32 vcc, v3, v0
	v_add_u32_e32 v4, 1, v2
	v_add_u32_e32 v1, 1, v1
	v_cndmask_b32_e32 v2, v2, v4, vcc
	v_sub_u32_e32 v4, v3, v0
	v_cndmask_b32_e32 v3, v3, v4, vcc
	v_cmp_ge_u32_e32 vcc, v3, v0
	v_add_u32_e32 v3, 1, v2
	s_nop 0
	v_cndmask_b32_e32 v2, v2, v3, vcc
	v_mul_lo_u32 v3, v0, v2
	v_add_u32_e32 v0, v3, v0
	v_mov_b32_e32 v5, v0
	v_cmp_ne_u32_e32 vcc, v1, v0
	v_mov_b64_e32 v[0:1], s[8:9]
	s_and_saveexec_b64 s[14:15], vcc
	s_cbranch_execz .LBB0_968
	v_readlane_b32 s8, v252, 7
	v_readlane_b32 s9, v252, 8
	s_mov_b64 s[18:19], 0
	s_nop 3
	global_load_dword v0, v33, s[8:9] sc1
	s_waitcnt vmcnt(0)
	v_cmp_lt_u32_e32 vcc, v0, v5
	s_and_saveexec_b64 s[16:17], vcc
	s_cbranch_execz .LBB0_967
	s_mov_b32 s2, 1
	s_branch .LBB0_960

.LBB0_970:
	s_or_b64 exec, exec, s[14:15]
	s_mov_b64 s[14:15], exec
	v_mbcnt_lo_u32_b32 v0, s14, 0
	v_mbcnt_hi_u32_b32 v0, s15, v0
	v_cmp_eq_u32_e32 vcc, 0, v0
	s_waitcnt vmcnt(0)
	s_and_saveexec_b64 s[16:17], vcc
	s_cbranch_execz .LBB0_972
	s_bcnt1_i32_b64 s2, s[14:15]
	v_mov_b32_e32 v0, s2
	global_atomic_add v223, v0, s[12:13] offset:1024

.LBB0_1610:
	s_or_b64 exec, exec, s[18:19]
	buffer_inv sc1
	s_waitcnt vmcnt(0)
	v_readfirstlane_b32 s2, v2
	v_cvt_f32_u32_e32 v2, v0
	v_sub_u32_e32 v3, 0, v0
	v_add_u32_e32 v1, s2, v1
	v_readlane_b32 s8, v252, 9
	v_rcp_iflag_f32_e32 v2, v2
	v_readlane_b32 s9, v252, 10
	s_mov_b64 s[18:19], -1
	v_mul_f32_e32 v2, 0x4f7ffffe, v2
	v_cvt_u32_f32_e32 v2, v2
	v_mul_lo_u32 v3, v3, v2
	v_mul_hi_u32 v3, v2, v3
	v_add_u32_e32 v2, v2, v3
	v_mul_hi_u32 v2, v1, v2
	v_mul_lo_u32 v3, v2, v0
	v_sub_u32_e32 v3, v1, v3
	v_cmp_ge_u32_e32 vcc, v3, v0
	v_add_u32_e32 v4, 1, v2
	v_add_u32_e32 v1, 1, v1
	v_cndmask_b32_e32 v2, v2, v4, vcc
	v_sub_u32_e32 v4, v3, v0
	v_cndmask_b32_e32 v3, v3, v4, vcc
	v_cmp_ge_u32_e32 vcc, v3, v0
	v_add_u32_e32 v3, 1, v2
	s_nop 0
	v_cndmask_b32_e32 v2, v2, v3, vcc
	v_mul_lo_u32 v3, v0, v2
	v_add_u32_e32 v0, v3, v0
	v_mov_b32_e32 v5, v0
	v_cmp_ne_u32_e32 vcc, v1, v0
	v_mov_b64_e32 v[0:1], s[8:9]
	s_and_saveexec_b64 s[16:17], vcc
	s_cbranch_execz .LBB0_1622
	v_readlane_b32 s8, v252, 7
	v_readlane_b32 s9, v252, 8
	s_mov_b64 s[20:21], 0
	s_nop 3
	global_load_dword v0, v33, s[8:9] sc1
	s_waitcnt vmcnt(0)
	v_cmp_lt_u32_e32 vcc, v0, v5
	s_and_saveexec_b64 s[18:19], vcc
	s_cbranch_execz .LBB0_1621
	s_mov_b32 s2, 1
	s_branch .LBB0_1614

.LBB0_1624:
	s_or_b64 exec, exec, s[16:17]
	s_mov_b64 s[16:17], exec
	v_mbcnt_lo_u32_b32 v0, s16, 0
	v_mbcnt_hi_u32_b32 v0, s17, v0
	v_cmp_eq_u32_e32 vcc, 0, v0
	s_waitcnt vmcnt(0)
	s_and_saveexec_b64 s[18:19], vcc
	s_cbranch_execz .LBB0_1626
	s_bcnt1_i32_b64 s2, s[16:17]
	v_mov_b32_e32 v0, s2
	global_atomic_add v223, v0, s[14:15] offset:1024

.LBB0_1730:
	s_or_b64 exec, exec, s[16:17]
	buffer_inv sc1
	s_waitcnt vmcnt(0)
	v_readfirstlane_b32 s8, v2
	v_cvt_f32_u32_e32 v2, v0
	v_sub_u32_e32 v3, 0, v0
	v_add_u32_e32 v1, s8, v1
	v_readlane_b32 s8, v252, 9
	v_rcp_iflag_f32_e32 v2, v2
	v_readlane_b32 s9, v252, 10
	s_mov_b64 s[16:17], -1
	v_mul_f32_e32 v2, 0x4f7ffffe, v2
	v_cvt_u32_f32_e32 v2, v2
	v_mul_lo_u32 v3, v3, v2
	v_mul_hi_u32 v3, v2, v3
	v_add_u32_e32 v2, v2, v3
	v_mul_hi_u32 v2, v1, v2
	v_mul_lo_u32 v3, v2, v0
	v_sub_u32_e32 v3, v1, v3
	v_cmp_ge_u32_e32 vcc, v3, v0
	v_add_u32_e32 v4, 1, v2
	v_add_u32_e32 v1, 1, v1
	v_cndmask_b32_e32 v2, v2, v4, vcc
	v_sub_u32_e32 v4, v3, v0
	v_cndmask_b32_e32 v3, v3, v4, vcc
	v_cmp_ge_u32_e32 vcc, v3, v0
	v_add_u32_e32 v3, 1, v2
	s_nop 0
	v_cndmask_b32_e32 v2, v2, v3, vcc
	v_mul_lo_u32 v3, v0, v2
	v_add_u32_e32 v0, v3, v0
	v_mov_b32_e32 v5, v0
	v_cmp_ne_u32_e32 vcc, v1, v0
	v_mov_b64_e32 v[0:1], s[8:9]
	s_and_saveexec_b64 s[14:15], vcc
	s_cbranch_execz .LBB0_1742
	v_readlane_b32 s8, v252, 7
	v_readlane_b32 s9, v252, 8
	s_mov_b64 s[18:19], 0
	s_nop 3
	global_load_dword v0, v33, s[8:9] sc1
	s_waitcnt vmcnt(0)
	v_cmp_lt_u32_e32 vcc, v0, v5
	s_and_saveexec_b64 s[16:17], vcc
	s_cbranch_execz .LBB0_1741
	s_mov_b32 s8, 1
	s_branch .LBB0_1734

.LBB0_1744:
	s_or_b64 exec, exec, s[14:15]
	s_mov_b64 s[14:15], exec
	v_mbcnt_lo_u32_b32 v0, s14, 0
	v_mbcnt_hi_u32_b32 v0, s15, v0
	v_cmp_eq_u32_e32 vcc, 0, v0
	s_waitcnt vmcnt(0)
	s_and_saveexec_b64 s[16:17], vcc
	s_cbranch_execnz .LBB0_1745
	s_getpc_b64 s[98:99]
